# v52_align0
# speedup vs baseline: 1.0060x; 1.0041x over previous
; #define PG8_STAGE(bufoff, gbase, voff) do { _Pragma("unroll") for (int _i = 0; _i < 2; ++_i) \
;         __builtin_amdgcn_global_load_lds((const unsigned*)((const char*)(gbase) + (voff)[_i]), (PG8_LAS unsigned*)(lds + (bufoff) + ldsw + _i * 8192), 16, 0, 0); } while (0)
; #define PG8_LDA(dst, b, h) do { _Pragma("unroll") for (int m = 0; m < 4; ++m) _Pragma("unroll") for (int k = 0; k < 2; ++k) dst[m][k] = *(const PG8_LAS bf16x8*)(lds + PG8_SA(b, h) + aoff + m * 2048 + k * 1024); } while (0)
; #define PG8_LDB(dst, b, h) do { _Pragma("unroll") for (int n = 0; n < 2; ++n) _Pragma("unroll") for (int k = 0; k < 2; ++k) dst[n][k] = *(const PG8_LAS bf16x8*)(lds + PG8_SB(b, h) + boff + n * 2048 + k * 1024); } while (0)
; #define PG8_MMA(ai, bj, At, Bt) do { __builtin_amdgcn_s_setprio(1); _Pragma("unroll") for (int m = 0; m < 4; ++m) _Pragma("unroll") for (int n = 0; n < 2; ++n) _Pragma("unroll") for (int k = 0; k < 2; ++k) \
;         acc[ai][bj][m][n] = __builtin_amdgcn_mfma_f32_16x16x32_bf16(Bt[n][k], At[m][k], acc[ai][bj][m][n], 0, 0, 0); __builtin_amdgcn_s_setprio(0); } while (0)
; #define PG8_WAIT_V(n) asm volatile("s_waitcnt vmcnt(" #n ")" ::: "memory")
; #define PG8_WAIT_L(n) asm volatile("s_waitcnt lgkmcnt(" #n ")" ::: "memory")
; #define PG8_BAR __builtin_amdgcn_s_barrier()
; #define PG8_SCHED __builtin_amdgcn_sched_barrier(0)
; template <class Epi, class Sched, bool ALIGN_EPI = false, bool SP2 = false>
; __device__ __forceinline__ void gemm_phase(PG8_LAS unsigned char* lds, const Gemm g, const Sched& S, const Epi& E, const int tid_in) {
;     ...
;         for (int t = 0; t < nt; t += 2) {
;             const bool last = (t == nt - 2);
;             const char* a1 = cA + (size_t)(t + 1) * kstep;
;             const char* a2 = last ? nA : cA + (size_t)(t + 2) * kstep; const char* b2 = last ? nB : cB + (size_t)(t + 2) * kstep;
;             const char* a3 = a2 + kstep; const char* b3 = b2 + kstep;
;             if (last && has_next) S.a_ready(nxt);
;             if constexpr (SP2) {
;             PG8_LDB(B0, 0, 0); PG8_LDB(B1, 0, 1); PG8_SCHED; PG8_LDA(At, 0, 0); PG8_STAGE(PG8_SA(1, 1), a1 + hstep, voffA);
;             PG8_WAIT_V(8); PG8_WAIT_L(0); PG8_BAR; PG8_MMA(0, 0, At, B0); PG8_MMA(0, 1, At, B1); PG8_BAR; PG8_SCHED;
.LBB0_24:
	s_ashr_i32 s25, s24, 31
	s_lshl_b64 s[26:27], s[24:25], 20
	s_add_u32 s26, s48, s26
	s_addc_u32 s27, s49, s27
	s_and_b64 s[36:37], s[6:7], exec
	s_cselect_b32 s25, s27, s41
	s_cselect_b32 s72, s26, s40
	s_ashr_i32 s17, s16, 31
	s_lshl_b64 s[36:37], s[16:17], 20
	s_add_u32 s36, s46, s36
	s_addc_u32 s37, s47, s37
	s_and_b64 s[44:45], s[6:7], exec
	s_cselect_b32 s17, s37, s43
	s_cselect_b32 s83, s36, s42
	s_add_u32 s40, s40, 0x80080
	s_addc_u32 s41, s41, 0
	s_add_u32 s84, s42, 0x100
	v_mov_b32_e32 v2, 0
	s_addc_u32 s85, s43, 0
	s_mov_b32 s86, -2
	v_mov_b32_e32 v3, v2
	v_mov_b32_e32 v4, v2
	v_mov_b32_e32 v5, v2
	v_mov_b32_e32 v10, v2
	v_mov_b32_e32 v11, v2
	v_mov_b32_e32 v12, v2
	v_mov_b32_e32 v13, v2
	v_mov_b32_e32 v18, v2
	v_mov_b32_e32 v19, v2
	v_mov_b32_e32 v20, v2
	v_mov_b32_e32 v21, v2
	v_mov_b32_e32 v26, v2
	v_mov_b32_e32 v27, v2
	v_mov_b32_e32 v28, v2
	v_mov_b32_e32 v29, v2
	v_mov_b32_e32 v34, v2
	v_mov_b32_e32 v35, v2
	v_mov_b32_e32 v36, v2
	v_mov_b32_e32 v37, v2
	v_mov_b32_e32 v42, v2
	v_mov_b32_e32 v43, v2
	v_mov_b32_e32 v44, v2
	v_mov_b32_e32 v45, v2
	v_mov_b32_e32 v50, v2
	v_mov_b32_e32 v51, v2
	v_mov_b32_e32 v52, v2
	v_mov_b32_e32 v53, v2
	v_mov_b32_e32 v58, v2
	v_mov_b32_e32 v59, v2
	v_mov_b32_e32 v60, v2
	v_mov_b32_e32 v61, v2
	v_mov_b32_e32 v6, v2
	v_mov_b32_e32 v7, v2
	v_mov_b32_e32 v8, v2
	v_mov_b32_e32 v9, v2
	v_mov_b32_e32 v14, v2
	v_mov_b32_e32 v15, v2
	v_mov_b32_e32 v16, v2
	v_mov_b32_e32 v17, v2
	v_mov_b32_e32 v22, v2
	v_mov_b32_e32 v23, v2
	v_mov_b32_e32 v24, v2
	v_mov_b32_e32 v25, v2
	v_mov_b32_e32 v30, v2
	v_mov_b32_e32 v31, v2
	v_mov_b32_e32 v32, v2
	v_mov_b32_e32 v33, v2
	v_mov_b32_e32 v38, v2
	v_mov_b32_e32 v39, v2
	v_mov_b32_e32 v40, v2
	v_mov_b32_e32 v41, v2
	v_mov_b32_e32 v46, v2
	v_mov_b32_e32 v47, v2
	v_mov_b32_e32 v48, v2
	v_mov_b32_e32 v49, v2
	v_mov_b32_e32 v54, v2
	v_mov_b32_e32 v55, v2
	v_mov_b32_e32 v56, v2
	v_mov_b32_e32 v57, v2
	v_mov_b32_e32 v62, v2
	v_mov_b32_e32 v63, v2
	v_mov_b32_e32 v64, v2
	v_mov_b32_e32 v65, v2
	v_mov_b32_e32 v66, v2
	v_mov_b32_e32 v67, v2
	v_mov_b32_e32 v68, v2
	v_mov_b32_e32 v69, v2
	v_mov_b32_e32 v74, v2
	v_mov_b32_e32 v75, v2
	v_mov_b32_e32 v76, v2
	v_mov_b32_e32 v77, v2
	v_mov_b32_e32 v82, v2
	v_mov_b32_e32 v83, v2
	v_mov_b32_e32 v84, v2
	v_mov_b32_e32 v85, v2
	v_mov_b32_e32 v90, v2
	v_mov_b32_e32 v91, v2
	v_mov_b32_e32 v92, v2
	v_mov_b32_e32 v93, v2
	v_mov_b32_e32 v98, v2
	v_mov_b32_e32 v99, v2
	v_mov_b32_e32 v100, v2
	v_mov_b32_e32 v101, v2
	v_mov_b32_e32 v106, v2
	v_mov_b32_e32 v107, v2
	v_mov_b32_e32 v108, v2
	v_mov_b32_e32 v109, v2
	v_mov_b32_e32 v114, v2
	v_mov_b32_e32 v115, v2
	v_mov_b32_e32 v116, v2
	v_mov_b32_e32 v117, v2
	v_mov_b32_e32 v122, v2
	v_mov_b32_e32 v123, v2
	v_mov_b32_e32 v124, v2
	v_mov_b32_e32 v125, v2
	v_mov_b32_e32 v70, v2
	v_mov_b32_e32 v71, v2
	v_mov_b32_e32 v72, v2
	v_mov_b32_e32 v73, v2
	v_mov_b32_e32 v78, v2
	v_mov_b32_e32 v79, v2
	v_mov_b32_e32 v80, v2
	v_mov_b32_e32 v81, v2
	v_mov_b32_e32 v86, v2
	v_mov_b32_e32 v87, v2
	v_mov_b32_e32 v88, v2
	v_mov_b32_e32 v89, v2
	v_mov_b32_e32 v94, v2
	v_mov_b32_e32 v95, v2
	v_mov_b32_e32 v96, v2
	v_mov_b32_e32 v97, v2
	v_mov_b32_e32 v102, v2
	v_mov_b32_e32 v103, v2
	v_mov_b32_e32 v104, v2
	v_mov_b32_e32 v105, v2
	v_mov_b32_e32 v110, v2
	v_mov_b32_e32 v111, v2
	v_mov_b32_e32 v112, v2
	v_mov_b32_e32 v113, v2
	v_mov_b32_e32 v118, v2
	v_mov_b32_e32 v119, v2
	v_mov_b32_e32 v120, v2
	v_mov_b32_e32 v121, v2
	v_mov_b32_e32 v126, v2
	v_mov_b32_e32 v127, v2
	v_mov_b32_e32 v128, v2
	v_mov_b32_e32 v129, v2
	s_nop 0
	s_nop 0
	s_nop 0
	s_nop 0
	s_nop 0
	s_nop 0
	s_nop 0
.LBB0_25:
	s_add_u32 s31, s40, 0xfff80080
	s_addc_u32 s42, s41, -1
	s_add_i32 s87, 0, 0x10000
	s_cmp_eq_u32 s86, 28
	s_cselect_b32 s45, s25, s42
	s_cselect_b32 s44, s72, s31
	s_cselect_b32 s43, s17, s85
	s_cselect_b32 s42, s83, s84
	s_add_i32 s31, 0, 0x14000
	v_add_u32_e32 v156, s87, v142
	v_add_u32_e32 v160, s31, v142
	ds_read_b128 v[144:147], v156
	ds_read_b128 v[148:151], v156 offset:1024
	ds_read_b128 v[152:155], v156 offset:2048
	ds_read_b128 v[156:159], v156 offset:3072
	ds_read_b128 v[176:179], v160
	ds_read_b128 v[180:183], v160 offset:1024
	ds_read_b128 v[184:187], v160 offset:2048
	ds_read_b128 v[188:191], v160 offset:3072
	v_lshl_add_u64 v[160:161], s[40:41], 0, v[136:137]
	s_add_i32 m0, s52, 0xc000
	ds_read_b128 v[192:195], v143
	ds_read_b128 v[196:199], v143 offset:1024
	ds_read_b128 v[200:203], v143 offset:2048
	ds_read_b128 v[204:207], v143 offset:3072
	ds_read_b128 v[208:211], v143 offset:4096
	ds_read_b128 v[212:215], v143 offset:5120
	ds_read_b128 v[216:219], v143 offset:6144
	ds_read_b128 v[220:223], v143 offset:7168
	global_load_lds_dwordx4 v[160:161], off
	v_lshl_add_u64 v[160:161], s[40:41], 0, v[138:139]
	s_add_i32 m0, s52, 0xe000
	s_nop 0
	global_load_lds_dwordx4 v[160:161], off
	s_waitcnt vmcnt(8)
	s_waitcnt lgkmcnt(0)
	s_barrier
; #define PG8_STAGE(bufoff, gbase, voff) do { _Pragma("unroll") for (int _i = 0; _i < 2; ++_i) \
;         __builtin_amdgcn_global_load_lds((const unsigned*)((const char*)(gbase) + (voff)[_i]), (PG8_LAS unsigned*)(lds + (bufoff) + ldsw + _i * 8192), 16, 0, 0); } while (0)
; #define PG8_LDA(dst, b, h) do { _Pragma("unroll") for (int m = 0; m < 4; ++m) _Pragma("unroll") for (int k = 0; k < 2; ++k) dst[m][k] = *(const PG8_LAS bf16x8*)(lds + PG8_SA(b, h) + aoff + m * 2048 + k * 1024); } while (0)
; #define PG8_MMA(ai, bj, At, Bt) do { __builtin_amdgcn_s_setprio(1); _Pragma("unroll") for (int m = 0; m < 4; ++m) _Pragma("unroll") for (int n = 0; n < 2; ++n) _Pragma("unroll") for (int k = 0; k < 2; ++k) \
;         acc[ai][bj][m][n] = __builtin_amdgcn_mfma_f32_16x16x32_bf16(Bt[n][k], At[m][k], acc[ai][bj][m][n], 0, 0, 0); __builtin_amdgcn_s_setprio(0); } while (0)
; #define PG8_WAIT_V(n) asm volatile("s_waitcnt vmcnt(" #n ")" ::: "memory")
; #define PG8_WAIT_L(n) asm volatile("s_waitcnt lgkmcnt(" #n ")" ::: "memory")
; #define PG8_BAR __builtin_amdgcn_s_barrier()
; #define PG8_SCHED __builtin_amdgcn_sched_barrier(0)
; template <class Epi, class Sched, bool ALIGN_EPI = false, bool SP2 = false>
; __device__ __forceinline__ void gemm_phase(PG8_LAS unsigned char* lds, const Gemm g, const Sched& S, const Epi& E, const int tid_in) {
;     ...
;             PG8_WAIT_V(8); PG8_WAIT_L(0); PG8_BAR; PG8_MMA(0, 0, At, B0); PG8_MMA(0, 1, At, B1); PG8_BAR; PG8_SCHED;
;             PG8_LDA(At, 0, 1); PG8_STAGE(PG8_SB(0, 0), b2, voffB); PG8_STAGE(PG8_SB(0, 1), b2 + hstep, voffB); PG8_STAGE(PG8_SA(0, 0), a2, voffA);
;             PG8_WAIT_V(8); PG8_WAIT_L(0); PG8_BAR; PG8_MMA(1, 0, At, B0); PG8_MMA(1, 1, At, B1); PG8_BAR; PG8_SCHED;
	s_setprio 1
	s_waitcnt lgkmcnt(0)
	v_mfma_f32_16x16x32_bf16 v[126:129], v[144:147], v[192:195], v[126:129]
	v_mfma_f32_16x16x32_bf16 v[118:121], v[152:155], v[192:195], v[118:121]
	v_mfma_f32_16x16x32_bf16 v[110:113], v[144:147], v[200:203], v[110:113]
	v_mfma_f32_16x16x32_bf16 v[102:105], v[152:155], v[200:203], v[102:105]
	v_mfma_f32_16x16x32_bf16 v[94:97], v[144:147], v[208:211], v[94:97]
	v_mfma_f32_16x16x32_bf16 v[86:89], v[152:155], v[208:211], v[86:89]
	v_mfma_f32_16x16x32_bf16 v[78:81], v[144:147], v[216:219], v[78:81]
	v_mfma_f32_16x16x32_bf16 v[70:73], v[152:155], v[216:219], v[70:73]
	v_mfma_f32_16x16x32_bf16 v[126:129], v[148:151], v[196:199], v[126:129]
	v_mfma_f32_16x16x32_bf16 v[118:121], v[156:159], v[196:199], v[118:121]
	v_mfma_f32_16x16x32_bf16 v[110:113], v[148:151], v[204:207], v[110:113]
	v_mfma_f32_16x16x32_bf16 v[102:105], v[156:159], v[204:207], v[102:105]
	v_mfma_f32_16x16x32_bf16 v[94:97], v[148:151], v[212:215], v[94:97]
	v_mfma_f32_16x16x32_bf16 v[86:89], v[156:159], v[212:215], v[86:89]
	v_mfma_f32_16x16x32_bf16 v[78:81], v[148:151], v[220:223], v[78:81]
	v_mfma_f32_16x16x32_bf16 v[70:73], v[156:159], v[220:223], v[70:73]
	s_setprio 0
	s_setprio 1
	v_mfma_f32_16x16x32_bf16 v[122:125], v[176:179], v[192:195], v[122:125]
	v_mfma_f32_16x16x32_bf16 v[114:117], v[184:187], v[192:195], v[114:117]
	v_mfma_f32_16x16x32_bf16 v[106:109], v[176:179], v[200:203], v[106:109]
	v_mfma_f32_16x16x32_bf16 v[98:101], v[184:187], v[200:203], v[98:101]
	v_mfma_f32_16x16x32_bf16 v[90:93], v[176:179], v[208:211], v[90:93]
	v_mfma_f32_16x16x32_bf16 v[82:85], v[184:187], v[208:211], v[82:85]
	v_mfma_f32_16x16x32_bf16 v[74:77], v[176:179], v[216:219], v[74:77]
	v_mfma_f32_16x16x32_bf16 v[66:69], v[184:187], v[216:219], v[66:69]
	v_mfma_f32_16x16x32_bf16 v[122:125], v[180:183], v[196:199], v[122:125]
	v_mfma_f32_16x16x32_bf16 v[114:117], v[188:191], v[196:199], v[114:117]
	v_mfma_f32_16x16x32_bf16 v[106:109], v[180:183], v[204:207], v[106:109]
	v_mfma_f32_16x16x32_bf16 v[98:101], v[188:191], v[204:207], v[98:101]
	v_mfma_f32_16x16x32_bf16 v[90:93], v[180:183], v[212:215], v[90:93]
	v_mfma_f32_16x16x32_bf16 v[82:85], v[188:191], v[212:215], v[82:85]
	v_mfma_f32_16x16x32_bf16 v[74:77], v[180:183], v[220:223], v[74:77]
	v_mfma_f32_16x16x32_bf16 v[66:69], v[188:191], v[220:223], v[66:69]
	s_setprio 0
	s_barrier
	s_add_i32 s87, s87, s50
	v_lshl_add_u64 v[160:161], s[42:43], 0, v[0:1]
	s_mov_b32 m0, s87
	ds_read_b128 v[192:195], v143 offset:16384
	ds_read_b128 v[196:199], v143 offset:17408
	ds_read_b128 v[200:203], v143 offset:18432
	ds_read_b128 v[204:207], v143 offset:19456
	ds_read_b128 v[208:211], v143 offset:20480
	ds_read_b128 v[212:215], v143 offset:21504
	ds_read_b128 v[216:219], v143 offset:22528
	ds_read_b128 v[220:223], v143 offset:23552
	global_load_lds_dwordx4 v[160:161], off
	s_add_i32 m0, s87, 0x2000
	s_add_u32 s88, s42, 0x80000
	v_lshl_add_u64 v[224:225], s[42:43], 0, v[130:131]
	s_addc_u32 s89, s43, 0
	s_add_i32 s31, s31, s50
	global_load_lds_dwordx4 v[224:225], off
	v_lshl_add_u64 v[226:227], s[88:89], 0, v[0:1]
	s_mov_b32 m0, s31
	v_lshl_add_u64 v[228:229], s[44:45], 0, v[132:133]
	global_load_lds_dwordx4 v[226:227], off
	v_lshl_add_u64 v[226:227], s[88:89], 0, v[130:131]
	s_add_i32 m0, s31, 0x2000
	s_nop 0
	global_load_lds_dwordx4 v[226:227], off
	v_lshl_add_u64 v[226:227], s[44:45], 0, v[134:135]
	s_mov_b32 m0, s52
	s_nop 0
	global_load_lds_dwordx4 v[226:227], off
	s_mov_b32 m0, s53
	s_nop 0
	global_load_lds_dwordx4 v[228:229], off
	s_waitcnt vmcnt(8)
	s_waitcnt lgkmcnt(0)
	s_barrier
	s_setprio 1
	s_waitcnt lgkmcnt(0)
	v_mfma_f32_16x16x32_bf16 v[62:65], v[144:147], v[192:195], v[62:65]
	v_mfma_f32_16x16x32_bf16 v[54:57], v[152:155], v[192:195], v[54:57]
	v_mfma_f32_16x16x32_bf16 v[46:49], v[144:147], v[200:203], v[46:49]
	v_mfma_f32_16x16x32_bf16 v[38:41], v[152:155], v[200:203], v[38:41]
	v_mfma_f32_16x16x32_bf16 v[30:33], v[144:147], v[208:211], v[30:33]
	v_mfma_f32_16x16x32_bf16 v[22:25], v[152:155], v[208:211], v[22:25]
	v_mfma_f32_16x16x32_bf16 v[14:17], v[144:147], v[216:219], v[14:17]
	v_mfma_f32_16x16x32_bf16 v[6:9], v[152:155], v[216:219], v[6:9]
	v_mfma_f32_16x16x32_bf16 v[62:65], v[148:151], v[196:199], v[62:65]
	v_mfma_f32_16x16x32_bf16 v[54:57], v[156:159], v[196:199], v[54:57]
	v_mfma_f32_16x16x32_bf16 v[46:49], v[148:151], v[204:207], v[46:49]
	v_mfma_f32_16x16x32_bf16 v[38:41], v[156:159], v[204:207], v[38:41]
	v_mfma_f32_16x16x32_bf16 v[30:33], v[148:151], v[212:215], v[30:33]
	v_mfma_f32_16x16x32_bf16 v[22:25], v[156:159], v[212:215], v[22:25]
	v_mfma_f32_16x16x32_bf16 v[14:17], v[148:151], v[220:223], v[14:17]
	v_mfma_f32_16x16x32_bf16 v[6:9], v[156:159], v[220:223], v[6:9]
	s_setprio 0
	s_setprio 1
	v_mfma_f32_16x16x32_bf16 v[58:61], v[176:179], v[192:195], v[58:61]
	v_mfma_f32_16x16x32_bf16 v[50:53], v[184:187], v[192:195], v[50:53]
	v_mfma_f32_16x16x32_bf16 v[42:45], v[176:179], v[200:203], v[42:45]
	v_mfma_f32_16x16x32_bf16 v[34:37], v[184:187], v[200:203], v[34:37]
	v_mfma_f32_16x16x32_bf16 v[26:29], v[176:179], v[208:211], v[26:29]
	v_mfma_f32_16x16x32_bf16 v[18:21], v[184:187], v[208:211], v[18:21]
	v_mfma_f32_16x16x32_bf16 v[10:13], v[176:179], v[216:219], v[10:13]
	v_mfma_f32_16x16x32_bf16 v[2:5], v[184:187], v[216:219], v[2:5]
	v_mfma_f32_16x16x32_bf16 v[58:61], v[180:183], v[196:199], v[58:61]
	v_mfma_f32_16x16x32_bf16 v[50:53], v[188:191], v[196:199], v[50:53]
	v_mfma_f32_16x16x32_bf16 v[42:45], v[180:183], v[204:207], v[42:45]
	v_mfma_f32_16x16x32_bf16 v[34:37], v[188:191], v[204:207], v[34:37]
	v_mfma_f32_16x16x32_bf16 v[26:29], v[180:183], v[212:215], v[26:29]
	v_mfma_f32_16x16x32_bf16 v[18:21], v[188:191], v[212:215], v[18:21]
	v_mfma_f32_16x16x32_bf16 v[10:13], v[180:183], v[220:223], v[10:13]
	v_mfma_f32_16x16x32_bf16 v[2:5], v[188:191], v[220:223], v[2:5]
	s_setprio 0
	s_barrier
; #define PG8_STAGE(bufoff, gbase, voff) do { _Pragma("unroll") for (int _i = 0; _i < 2; ++_i) \
;         __builtin_amdgcn_global_load_lds((const unsigned*)((const char*)(gbase) + (voff)[_i]), (PG8_LAS unsigned*)(lds + (bufoff) + ldsw + _i * 8192), 16, 0, 0); } while (0)
; #define PG8_LDA(dst, b, h) do { _Pragma("unroll") for (int m = 0; m < 4; ++m) _Pragma("unroll") for (int k = 0; k < 2; ++k) dst[m][k] = *(const PG8_LAS bf16x8*)(lds + PG8_SA(b, h) + aoff + m * 2048 + k * 1024); } while (0)
; #define PG8_LDB(dst, b, h) do { _Pragma("unroll") for (int n = 0; n < 2; ++n) _Pragma("unroll") for (int k = 0; k < 2; ++k) dst[n][k] = *(const PG8_LAS bf16x8*)(lds + PG8_SB(b, h) + boff + n * 2048 + k * 1024); } while (0)
; #define PG8_MMA(ai, bj, At, Bt) do { __builtin_amdgcn_s_setprio(1); _Pragma("unroll") for (int m = 0; m < 4; ++m) _Pragma("unroll") for (int n = 0; n < 2; ++n) _Pragma("unroll") for (int k = 0; k < 2; ++k) \
;         acc[ai][bj][m][n] = __builtin_amdgcn_mfma_f32_16x16x32_bf16(Bt[n][k], At[m][k], acc[ai][bj][m][n], 0, 0, 0); __builtin_amdgcn_s_setprio(0); } while (0)
; #define PG8_WAIT_V(n) asm volatile("s_waitcnt vmcnt(" #n ")" ::: "memory")
; #define PG8_WAIT_L(n) asm volatile("s_waitcnt lgkmcnt(" #n ")" ::: "memory")
; #define PG8_BAR __builtin_amdgcn_s_barrier()
; #define PG8_SCHED __builtin_amdgcn_sched_barrier(0)
; template <class Epi, class Sched, bool ALIGN_EPI = false, bool SP2 = false>
; __device__ __forceinline__ void gemm_phase(PG8_LAS unsigned char* lds, const Gemm g, const Sched& S, const Epi& E, const int tid_in) {
;     ...
;             PG8_LDB(B0, 1, 0); PG8_LDB(B1, 1, 1); PG8_SCHED; PG8_LDA(At, 1, 0); PG8_STAGE(PG8_SA(0, 1), a2 + hstep, voffA);
;             PG8_WAIT_V(8); PG8_WAIT_L(0); PG8_BAR; PG8_MMA(0, 0, At, B0); PG8_MMA(0, 1, At, B1); PG8_BAR; PG8_SCHED;
	s_add_i32 s31, 0, 0x18000
	s_add_i32 s87, 0, 0x1c000
	v_add_u32_e32 v156, s31, v142
	v_add_u32_e32 v171, s87, v142
	ds_read_b128 v[144:147], v156
	ds_read_b128 v[148:151], v156 offset:1024
	ds_read_b128 v[152:155], v156 offset:2048
	ds_read_b128 v[156:159], v156 offset:3072
	ds_read_b128 v[176:179], v171
	ds_read_b128 v[180:183], v171 offset:1024
	ds_read_b128 v[184:187], v171 offset:2048
	ds_read_b128 v[188:191], v171 offset:3072
	s_add_u32 s44, s44, 0x80000
	s_addc_u32 s45, s45, 0
	s_mov_b32 m0, s54
	v_lshl_add_u64 v[240:241], s[44:45], 0, v[134:135]
	ds_read_b128 v[192:195], v143 offset:32768
	ds_read_b128 v[196:199], v143 offset:33792
	ds_read_b128 v[200:203], v143 offset:34816
	ds_read_b128 v[204:207], v143 offset:35840
	ds_read_b128 v[208:211], v143 offset:36864
	ds_read_b128 v[212:215], v143 offset:37888
	ds_read_b128 v[216:219], v143 offset:38912
	ds_read_b128 v[220:223], v143 offset:39936
	global_load_lds_dwordx4 v[240:241], off
	v_lshl_add_u64 v[240:241], s[44:45], 0, v[132:133]
	s_mov_b32 m0, s55
	s_nop 0
	global_load_lds_dwordx4 v[240:241], off
	s_waitcnt vmcnt(8)
	s_waitcnt lgkmcnt(0)
	s_barrier
	s_setprio 1
	s_waitcnt lgkmcnt(0)
	v_mfma_f32_16x16x32_bf16 v[126:129], v[144:147], v[192:195], v[126:129]
	v_mfma_f32_16x16x32_bf16 v[118:121], v[152:155], v[192:195], v[118:121]
	v_mfma_f32_16x16x32_bf16 v[110:113], v[144:147], v[200:203], v[110:113]
	v_mfma_f32_16x16x32_bf16 v[102:105], v[152:155], v[200:203], v[102:105]
	v_mfma_f32_16x16x32_bf16 v[94:97], v[144:147], v[208:211], v[94:97]
	v_mfma_f32_16x16x32_bf16 v[86:89], v[152:155], v[208:211], v[86:89]
	v_mfma_f32_16x16x32_bf16 v[78:81], v[144:147], v[216:219], v[78:81]
	v_mfma_f32_16x16x32_bf16 v[70:73], v[152:155], v[216:219], v[70:73]
	v_mfma_f32_16x16x32_bf16 v[126:129], v[148:151], v[196:199], v[126:129]
	v_mfma_f32_16x16x32_bf16 v[118:121], v[156:159], v[196:199], v[118:121]
	v_mfma_f32_16x16x32_bf16 v[110:113], v[148:151], v[204:207], v[110:113]
	v_mfma_f32_16x16x32_bf16 v[102:105], v[156:159], v[204:207], v[102:105]
	v_mfma_f32_16x16x32_bf16 v[94:97], v[148:151], v[212:215], v[94:97]
	v_mfma_f32_16x16x32_bf16 v[86:89], v[156:159], v[212:215], v[86:89]
	v_mfma_f32_16x16x32_bf16 v[78:81], v[148:151], v[220:223], v[78:81]
	v_mfma_f32_16x16x32_bf16 v[70:73], v[156:159], v[220:223], v[70:73]
	s_setprio 0
	s_setprio 1
	v_mfma_f32_16x16x32_bf16 v[122:125], v[176:179], v[192:195], v[122:125]
	v_mfma_f32_16x16x32_bf16 v[114:117], v[184:187], v[192:195], v[114:117]
	v_mfma_f32_16x16x32_bf16 v[106:109], v[176:179], v[200:203], v[106:109]
	v_mfma_f32_16x16x32_bf16 v[98:101], v[184:187], v[200:203], v[98:101]
	v_mfma_f32_16x16x32_bf16 v[90:93], v[176:179], v[208:211], v[90:93]
	v_mfma_f32_16x16x32_bf16 v[82:85], v[184:187], v[208:211], v[82:85]
	v_mfma_f32_16x16x32_bf16 v[74:77], v[176:179], v[216:219], v[74:77]
	v_mfma_f32_16x16x32_bf16 v[66:69], v[184:187], v[216:219], v[66:69]
	v_mfma_f32_16x16x32_bf16 v[122:125], v[180:183], v[196:199], v[122:125]
	v_mfma_f32_16x16x32_bf16 v[114:117], v[188:191], v[196:199], v[114:117]
	v_mfma_f32_16x16x32_bf16 v[106:109], v[180:183], v[204:207], v[106:109]
	v_mfma_f32_16x16x32_bf16 v[98:101], v[188:191], v[204:207], v[98:101]
	v_mfma_f32_16x16x32_bf16 v[90:93], v[180:183], v[212:215], v[90:93]
	v_mfma_f32_16x16x32_bf16 v[82:85], v[188:191], v[212:215], v[82:85]
	v_mfma_f32_16x16x32_bf16 v[74:77], v[180:183], v[220:223], v[74:77]
	v_mfma_f32_16x16x32_bf16 v[66:69], v[188:191], v[220:223], v[66:69]
	s_setprio 0
	s_barrier
; #define PG8_STAGE(bufoff, gbase, voff) do { _Pragma("unroll") for (int _i = 0; _i < 2; ++_i) \
;         __builtin_amdgcn_global_load_lds((const unsigned*)((const char*)(gbase) + (voff)[_i]), (PG8_LAS unsigned*)(lds + (bufoff) + ldsw + _i * 8192), 16, 0, 0); } while (0)
; #define PG8_LDA(dst, b, h) do { _Pragma("unroll") for (int m = 0; m < 4; ++m) _Pragma("unroll") for (int k = 0; k < 2; ++k) dst[m][k] = *(const PG8_LAS bf16x8*)(lds + PG8_SA(b, h) + aoff + m * 2048 + k * 1024); } while (0)
; #define PG8_MMA(ai, bj, At, Bt) do { __builtin_amdgcn_s_setprio(1); _Pragma("unroll") for (int m = 0; m < 4; ++m) _Pragma("unroll") for (int n = 0; n < 2; ++n) _Pragma("unroll") for (int k = 0; k < 2; ++k) \
;         acc[ai][bj][m][n] = __builtin_amdgcn_mfma_f32_16x16x32_bf16(Bt[n][k], At[m][k], acc[ai][bj][m][n], 0, 0, 0); __builtin_amdgcn_s_setprio(0); } while (0)
; #define PG8_WAIT_V(n) asm volatile("s_waitcnt vmcnt(" #n ")" ::: "memory")
; #define PG8_WAIT_L(n) asm volatile("s_waitcnt lgkmcnt(" #n ")" ::: "memory")
; #define PG8_BAR __builtin_amdgcn_s_barrier()
; #define PG8_SCHED __builtin_amdgcn_sched_barrier(0)
; template <class Epi, class Sched, bool ALIGN_EPI = false, bool SP2 = false>
; __device__ __forceinline__ void gemm_phase(PG8_LAS unsigned char* lds, const Gemm g, const Sched& S, const Epi& E, const int tid_in) {
;     ...
;             PG8_LDA(At, 1, 1); PG8_STAGE(PG8_SB(1, 0), b3, voffB); PG8_STAGE(PG8_SB(1, 1), b3 + hstep, voffB); PG8_STAGE(PG8_SA(1, 0), a3, voffA);
;             PG8_WAIT_V(8); PG8_WAIT_L(0); PG8_BAR; PG8_MMA(1, 0, At, B0); PG8_MMA(1, 1, At, B1); PG8_BAR; PG8_SCHED;
;     ...
;         if constexpr (ALIGN_EPI) { if (wr == 0) PG8_BAR; }
	s_add_i32 s31, s31, s50
	v_lshl_add_u64 v[160:161], v[160:161], 0, s[64:65]
	s_mov_b32 m0, s31
	ds_read_b128 v[192:195], v143 offset:49152
	ds_read_b128 v[196:199], v143 offset:50176
	ds_read_b128 v[200:203], v143 offset:51200
	ds_read_b128 v[204:207], v143 offset:52224
	ds_read_b128 v[208:211], v143 offset:53248
	ds_read_b128 v[212:215], v143 offset:54272
	ds_read_b128 v[216:219], v143 offset:55296
	ds_read_b128 v[220:223], v143 offset:56320
	global_load_lds_dwordx4 v[160:161], off
	s_add_i32 m0, s31, 0x2000
	s_add_u32 s42, s42, 0x80080
	v_lshl_add_u64 v[160:161], v[224:225], 0, s[64:65]
	s_addc_u32 s43, s43, 0
	s_add_i32 s31, s87, s50
	global_load_lds_dwordx4 v[160:161], off
	v_lshl_add_u64 v[160:161], s[42:43], 0, v[0:1]
	s_mov_b32 m0, s31
	s_nop 0
	global_load_lds_dwordx4 v[160:161], off
	v_lshl_add_u64 v[160:161], s[42:43], 0, v[130:131]
	s_add_i32 m0, s31, 0x2000
	s_nop 0
	global_load_lds_dwordx4 v[160:161], off
	v_lshl_add_u64 v[160:161], v[226:227], 0, s[64:65]
	s_mov_b32 m0, s66
	s_nop 0
	global_load_lds_dwordx4 v[160:161], off
	v_lshl_add_u64 v[160:161], v[228:229], 0, s[64:65]
	s_mov_b32 m0, s67
	s_nop 0
	global_load_lds_dwordx4 v[160:161], off
	s_waitcnt vmcnt(8)
	s_waitcnt lgkmcnt(0)
	s_barrier
	s_setprio 1
	s_waitcnt lgkmcnt(0)
	v_mfma_f32_16x16x32_bf16 v[62:65], v[144:147], v[192:195], v[62:65]
	v_mfma_f32_16x16x32_bf16 v[54:57], v[152:155], v[192:195], v[54:57]
	v_mfma_f32_16x16x32_bf16 v[46:49], v[144:147], v[200:203], v[46:49]
	v_mfma_f32_16x16x32_bf16 v[38:41], v[152:155], v[200:203], v[38:41]
	v_mfma_f32_16x16x32_bf16 v[30:33], v[144:147], v[208:211], v[30:33]
	v_mfma_f32_16x16x32_bf16 v[22:25], v[152:155], v[208:211], v[22:25]
	v_mfma_f32_16x16x32_bf16 v[14:17], v[144:147], v[216:219], v[14:17]
	v_mfma_f32_16x16x32_bf16 v[6:9], v[152:155], v[216:219], v[6:9]
	v_mfma_f32_16x16x32_bf16 v[62:65], v[148:151], v[196:199], v[62:65]
	v_mfma_f32_16x16x32_bf16 v[54:57], v[156:159], v[196:199], v[54:57]
	v_mfma_f32_16x16x32_bf16 v[46:49], v[148:151], v[204:207], v[46:49]
	v_mfma_f32_16x16x32_bf16 v[38:41], v[156:159], v[204:207], v[38:41]
	v_mfma_f32_16x16x32_bf16 v[30:33], v[148:151], v[212:215], v[30:33]
	v_mfma_f32_16x16x32_bf16 v[22:25], v[156:159], v[212:215], v[22:25]
	v_mfma_f32_16x16x32_bf16 v[14:17], v[148:151], v[220:223], v[14:17]
	v_mfma_f32_16x16x32_bf16 v[6:9], v[156:159], v[220:223], v[6:9]
	s_setprio 0
	s_setprio 1
	v_mfma_f32_16x16x32_bf16 v[58:61], v[176:179], v[192:195], v[58:61]
	v_mfma_f32_16x16x32_bf16 v[50:53], v[184:187], v[192:195], v[50:53]
	v_mfma_f32_16x16x32_bf16 v[42:45], v[176:179], v[200:203], v[42:45]
	v_mfma_f32_16x16x32_bf16 v[34:37], v[184:187], v[200:203], v[34:37]
	v_mfma_f32_16x16x32_bf16 v[26:29], v[176:179], v[208:211], v[26:29]
	v_mfma_f32_16x16x32_bf16 v[18:21], v[184:187], v[208:211], v[18:21]
	v_mfma_f32_16x16x32_bf16 v[10:13], v[176:179], v[216:219], v[10:13]
	v_mfma_f32_16x16x32_bf16 v[2:5], v[184:187], v[216:219], v[2:5]
	v_mfma_f32_16x16x32_bf16 v[58:61], v[180:183], v[196:199], v[58:61]
	v_mfma_f32_16x16x32_bf16 v[50:53], v[188:191], v[196:199], v[50:53]
	v_mfma_f32_16x16x32_bf16 v[42:45], v[180:183], v[204:207], v[42:45]
	v_mfma_f32_16x16x32_bf16 v[34:37], v[188:191], v[204:207], v[34:37]
	v_mfma_f32_16x16x32_bf16 v[26:29], v[180:183], v[212:215], v[26:29]
	v_mfma_f32_16x16x32_bf16 v[18:21], v[188:191], v[212:215], v[18:21]
	v_mfma_f32_16x16x32_bf16 v[10:13], v[180:183], v[220:223], v[10:13]
	v_mfma_f32_16x16x32_bf16 v[2:5], v[188:191], v[220:223], v[2:5]
	s_setprio 0
	s_barrier
	s_add_i32 s86, s86, 2
	s_add_u32 s40, s40, 0x100
	s_addc_u32 s41, s41, 0
	s_add_u32 s84, s84, 0x100
	s_addc_u32 s85, s85, 0
	s_cmp_gt_u32 s86, 29
	s_cbranch_scc0 .LBB0_25
	s_and_b64 vcc, exec, s[14:15]
	s_cbranch_vccz .LBB0_28
	s_barrier

; template <class Epi, class Sched, bool ALIGN_EPI = false, bool SP2 = false>
; __device__ __forceinline__ void gemm_phase(PG8_LAS unsigned char* lds, const Gemm g, const Sched& S, const Epi& E, const int tid_in) {
;     ...
;         const char* nA = has_next ? (const char*)g.A + (size_t)nxt.pm * tstep : cA; const char* nB = has_next ? (const char*)g.Bt + (size_t)nxt.pn * tstep : cB;
;         for (int t = 0; t < nt; t += 2) {
;             const bool last = (t == nt - 2);
;             const char* a1 = cA + (size_t)(t + 1) * kstep;
;             const char* a2 = last ? nA : cA + (size_t)(t + 2) * kstep; const char* b2 = last ? nB : cB + (size_t)(t + 2) * kstep;
;             const char* a3 = a2 + kstep; const char* b3 = b2 + kstep;
;     ...
;         for (int a = 0; a < 2; ++a)
; #pragma unroll
;             for (int b = 0; b < 2; ++b)
; #pragma unroll
;                 for (int m = 0; m < 4; ++m)
; #pragma unroll
;                     for (int n = 0; n < 2; ++n) acc[a][b][m][n] = (f32x4){0.f, 0.f, 0.f, 0.f};
.LBB0_57:
	s_ashr_i32 s37, s36, 31
	s_lshl_b64 s[38:39], s[36:37], 20
	s_add_u32 s38, s53, s38
	s_addc_u32 s39, s54, s39
	s_and_b64 s[40:41], s[6:7], exec
	s_cselect_b32 s37, s39, s45
	s_cselect_b32 s72, s38, s44
	s_ashr_i32 s27, s26, 31
	s_lshl_b64 s[40:41], s[26:27], 20
	s_add_u32 s40, s34, s40
	s_addc_u32 s41, s52, s41
	s_and_b64 s[48:49], s[6:7], exec
	s_cselect_b32 s27, s41, s47
	s_cselect_b32 s87, s40, s46
	s_add_u32 s88, s46, 0x100
	v_mov_b32_e32 v2, 0
	s_addc_u32 s89, s47, 0
	s_mov_b32 vcc_lo, -2
	v_mov_b32_e32 v3, v2
	v_mov_b32_e32 v4, v2
	v_mov_b32_e32 v5, v2
	v_mov_b32_e32 v6, v2
	v_mov_b32_e32 v7, v2
	v_mov_b32_e32 v8, v2
	v_mov_b32_e32 v9, v2
	v_mov_b32_e32 v14, v2
	v_mov_b32_e32 v15, v2
	v_mov_b32_e32 v16, v2
	v_mov_b32_e32 v17, v2
	v_mov_b32_e32 v18, v2
	v_mov_b32_e32 v19, v2
	v_mov_b32_e32 v20, v2
	v_mov_b32_e32 v21, v2
	v_mov_b32_e32 v30, v2
	v_mov_b32_e32 v31, v2
	v_mov_b32_e32 v32, v2
	v_mov_b32_e32 v33, v2
	v_mov_b32_e32 v34, v2
	v_mov_b32_e32 v35, v2
	v_mov_b32_e32 v36, v2
	v_mov_b32_e32 v37, v2
	v_mov_b32_e32 v46, v2
	v_mov_b32_e32 v47, v2
	v_mov_b32_e32 v48, v2
	v_mov_b32_e32 v49, v2
	v_mov_b32_e32 v50, v2
	v_mov_b32_e32 v51, v2
	v_mov_b32_e32 v52, v2
	v_mov_b32_e32 v53, v2
	v_mov_b32_e32 v10, v2
	v_mov_b32_e32 v11, v2
	v_mov_b32_e32 v12, v2
	v_mov_b32_e32 v13, v2
	v_mov_b32_e32 v22, v2
	v_mov_b32_e32 v23, v2
	v_mov_b32_e32 v24, v2
	v_mov_b32_e32 v25, v2
	v_mov_b32_e32 v26, v2
	v_mov_b32_e32 v27, v2
	v_mov_b32_e32 v28, v2
	v_mov_b32_e32 v29, v2
	v_mov_b32_e32 v38, v2
	v_mov_b32_e32 v39, v2
	v_mov_b32_e32 v40, v2
	v_mov_b32_e32 v41, v2
	v_mov_b32_e32 v42, v2
	v_mov_b32_e32 v43, v2
	v_mov_b32_e32 v44, v2
	v_mov_b32_e32 v45, v2
	v_mov_b32_e32 v54, v2
	v_mov_b32_e32 v55, v2
	v_mov_b32_e32 v56, v2
	v_mov_b32_e32 v57, v2
	v_mov_b32_e32 v58, v2
	v_mov_b32_e32 v59, v2
	v_mov_b32_e32 v60, v2
	v_mov_b32_e32 v61, v2
	v_mov_b32_e32 v62, v2
	v_mov_b32_e32 v63, v2
	v_mov_b32_e32 v64, v2
	v_mov_b32_e32 v65, v2
	v_mov_b32_e32 v66, v2
	v_mov_b32_e32 v67, v2
	v_mov_b32_e32 v68, v2
	v_mov_b32_e32 v69, v2
	v_mov_b32_e32 v70, v2
	v_mov_b32_e32 v71, v2
	v_mov_b32_e32 v72, v2
	v_mov_b32_e32 v73, v2
	v_mov_b32_e32 v78, v2
	v_mov_b32_e32 v79, v2
	v_mov_b32_e32 v80, v2
	v_mov_b32_e32 v81, v2
	v_mov_b32_e32 v82, v2
	v_mov_b32_e32 v83, v2
	v_mov_b32_e32 v84, v2
	v_mov_b32_e32 v85, v2
	v_mov_b32_e32 v94, v2
	v_mov_b32_e32 v95, v2
	v_mov_b32_e32 v96, v2
	v_mov_b32_e32 v97, v2
	v_mov_b32_e32 v98, v2
	v_mov_b32_e32 v99, v2
	v_mov_b32_e32 v100, v2
	v_mov_b32_e32 v101, v2
	v_mov_b32_e32 v110, v2
	v_mov_b32_e32 v111, v2
	v_mov_b32_e32 v112, v2
	v_mov_b32_e32 v113, v2
	v_mov_b32_e32 v114, v2
	v_mov_b32_e32 v115, v2
	v_mov_b32_e32 v116, v2
	v_mov_b32_e32 v117, v2
	v_mov_b32_e32 v74, v2
	v_mov_b32_e32 v75, v2
	v_mov_b32_e32 v76, v2
	v_mov_b32_e32 v77, v2
	v_mov_b32_e32 v86, v2
	v_mov_b32_e32 v87, v2
	v_mov_b32_e32 v88, v2
	v_mov_b32_e32 v89, v2
	v_mov_b32_e32 v90, v2
	v_mov_b32_e32 v91, v2
	v_mov_b32_e32 v92, v2
	v_mov_b32_e32 v93, v2
	v_mov_b32_e32 v102, v2
	v_mov_b32_e32 v103, v2
	v_mov_b32_e32 v104, v2
	v_mov_b32_e32 v105, v2
	v_mov_b32_e32 v106, v2
	v_mov_b32_e32 v107, v2
	v_mov_b32_e32 v108, v2
	v_mov_b32_e32 v109, v2
	v_mov_b32_e32 v118, v2
	v_mov_b32_e32 v119, v2
	v_mov_b32_e32 v120, v2
	v_mov_b32_e32 v121, v2
	v_mov_b32_e32 v122, v2
	v_mov_b32_e32 v123, v2
	v_mov_b32_e32 v124, v2
	v_mov_b32_e32 v125, v2
	v_mov_b32_e32 v126, v2
	v_mov_b32_e32 v127, v2
	v_mov_b32_e32 v128, v2
	v_mov_b32_e32 v129, v2
	s_nop 0
	s_nop 0
	s_nop 0
	s_nop 0
	s_nop 0
	s_nop 0
	s_nop 0
	s_nop 0
	s_nop 0
	s_nop 0
	s_nop 0
	s_nop 0
	s_nop 0

; #define PG8_STAGE(bufoff, gbase, voff) do { _Pragma("unroll") for (int _i = 0; _i < 2; ++_i) \
;         __builtin_amdgcn_global_load_lds((const unsigned*)((const char*)(gbase) + (voff)[_i]), (PG8_LAS unsigned*)(lds + (bufoff) + ldsw + _i * 8192), 16, 0, 0); } while (0)
; #define PG8_LDA(dst, b, h) do { _Pragma("unroll") for (int m = 0; m < 4; ++m) _Pragma("unroll") for (int k = 0; k < 2; ++k) dst[m][k] = *(const PG8_LAS bf16x8*)(lds + PG8_SA(b, h) + aoff + m * 2048 + k * 1024); } while (0)
; #define PG8_LDB(dst, b, h) do { _Pragma("unroll") for (int n = 0; n < 2; ++n) _Pragma("unroll") for (int k = 0; k < 2; ++k) dst[n][k] = *(const PG8_LAS bf16x8*)(lds + PG8_SB(b, h) + boff + n * 2048 + k * 1024); } while (0)
; #define PG8_MMA(ai, bj, At, Bt) do { __builtin_amdgcn_s_setprio(1); _Pragma("unroll") for (int m = 0; m < 4; ++m) _Pragma("unroll") for (int n = 0; n < 2; ++n) _Pragma("unroll") for (int k = 0; k < 2; ++k) \
;         acc[ai][bj][m][n] = __builtin_amdgcn_mfma_f32_16x16x32_bf16(Bt[n][k], At[m][k], acc[ai][bj][m][n], 0, 0, 0); __builtin_amdgcn_s_setprio(0); } while (0)
; #define PG8_WAIT_V(n) asm volatile("s_waitcnt vmcnt(" #n ")" ::: "memory")
; #define PG8_BAR __builtin_amdgcn_s_barrier()
; template <class Epi, class Sched, bool ALIGN_EPI = false, bool SP2 = false>
; __device__ __forceinline__ void gemm_phase(PG8_LAS unsigned char* lds, const Gemm g, const Sched& S, const Epi& E, const int tid_in) {
;     ...
;         for (int t = 0; t < nt; t += 2) {
;             const bool last = (t == nt - 2);
;             const char* a1 = cA + (size_t)(t + 1) * kstep;
;             const char* a2 = last ? nA : cA + (size_t)(t + 2) * kstep; const char* b2 = last ? nB : cB + (size_t)(t + 2) * kstep;
;             const char* a3 = a2 + kstep; const char* b3 = b2 + kstep;
;             if (last && has_next) S.a_ready(nxt);
;             if constexpr (SP2) {
;             PG8_LDB(B0, 0, 0); PG8_LDB(B1, 0, 1); PG8_SCHED; PG8_LDA(At, 0, 0); PG8_STAGE(PG8_SA(1, 1), a1 + hstep, voffA);
;             PG8_WAIT_V(8); PG8_WAIT_L(0); PG8_BAR; PG8_MMA(0, 0, At, B0); PG8_MMA(0, 1, At, B1); PG8_BAR; PG8_SCHED;
;             PG8_LDA(At, 0, 1); PG8_STAGE(PG8_SB(0, 0), b2, voffB); PG8_STAGE(PG8_SB(0, 1), b2 + hstep, voffB); PG8_STAGE(PG8_SA(0, 0), a2, voffA);
;             PG8_WAIT_V(8); PG8_WAIT_L(0); PG8_BAR; PG8_MMA(1, 0, At, B0); PG8_MMA(1, 1, At, B1); PG8_BAR; PG8_SCHED;
.Lrb_nozero:
	s_nop 0
	s_nop 0
	s_nop 0
	s_nop 0
	s_nop 0
	s_nop 0
	s_nop 0
	s_nop 0
	s_nop 0
	s_nop 0
	s_nop 0
	s_nop 0
.LBB0_86:
	s_add_u32 s46, s44, 0xfffe0080
	s_addc_u32 s47, s45, -1
	s_add_i32 s89, 0, 0x10000
	s_cmp_eq_u32 s88, 4
	s_cselect_b32 s49, s9, s47
	s_cselect_b32 s48, s27, s46
	s_cselect_b32 s47, s37, s87
	s_cselect_b32 s46, s43, s72
	s_add_i32 s31, 0, 0x14000
	v_add_u32_e32 v142, s89, v240
	v_add_u32_e32 v158, s31, v240
	ds_read_b128 v[130:133], v142
	ds_read_b128 v[134:137], v142 offset:1024
	ds_read_b128 v[138:141], v142 offset:2048
	ds_read_b128 v[142:145], v142 offset:3072
	ds_read_b128 v[146:149], v158
	ds_read_b128 v[150:153], v158 offset:1024
	ds_read_b128 v[154:157], v158 offset:2048
	ds_read_b128 v[158:161], v158 offset:3072
	v_lshl_add_u64 v[218:219], s[44:45], 0, v[182:183]
	s_add_i32 m0, s53, 0xc000
	ds_read_b128 v[186:189], v241
	ds_read_b128 v[190:193], v241 offset:1024
	ds_read_b128 v[194:197], v241 offset:2048
	ds_read_b128 v[198:201], v241 offset:3072
	ds_read_b128 v[202:205], v241 offset:4096
	ds_read_b128 v[206:209], v241 offset:5120
	ds_read_b128 v[210:213], v241 offset:6144
	ds_read_b128 v[214:217], v241 offset:7168
	global_load_lds_dwordx4 v[218:219], off
	v_lshl_add_u64 v[218:219], s[44:45], 0, v[184:185]
	s_add_i32 m0, s53, 0xe000
	s_nop 0
	global_load_lds_dwordx4 v[218:219], off
	s_waitcnt vmcnt(8)
	s_waitcnt lgkmcnt(0)
	s_barrier
	s_setprio 1
	s_waitcnt lgkmcnt(0)
	v_mfma_f32_16x16x32_bf16 v[126:129], v[130:133], v[186:189], v[126:129]
	v_mfma_f32_16x16x32_bf16 v[122:125], v[138:141], v[186:189], v[122:125]
	v_mfma_f32_16x16x32_bf16 v[110:113], v[130:133], v[194:197], v[110:113]
	v_mfma_f32_16x16x32_bf16 v[106:109], v[138:141], v[194:197], v[106:109]
	v_mfma_f32_16x16x32_bf16 v[94:97], v[130:133], v[202:205], v[94:97]
	v_mfma_f32_16x16x32_bf16 v[90:93], v[138:141], v[202:205], v[90:93]
	v_mfma_f32_16x16x32_bf16 v[78:81], v[130:133], v[210:213], v[78:81]
	v_mfma_f32_16x16x32_bf16 v[74:77], v[138:141], v[210:213], v[74:77]
	v_mfma_f32_16x16x32_bf16 v[126:129], v[134:137], v[190:193], v[126:129]
	v_mfma_f32_16x16x32_bf16 v[122:125], v[142:145], v[190:193], v[122:125]
	v_mfma_f32_16x16x32_bf16 v[110:113], v[134:137], v[198:201], v[110:113]
	v_mfma_f32_16x16x32_bf16 v[106:109], v[142:145], v[198:201], v[106:109]
	v_mfma_f32_16x16x32_bf16 v[94:97], v[134:137], v[206:209], v[94:97]
	v_mfma_f32_16x16x32_bf16 v[90:93], v[142:145], v[206:209], v[90:93]
	v_mfma_f32_16x16x32_bf16 v[78:81], v[134:137], v[214:217], v[78:81]
	v_mfma_f32_16x16x32_bf16 v[74:77], v[142:145], v[214:217], v[74:77]
	s_setprio 0
	s_setprio 1
	v_mfma_f32_16x16x32_bf16 v[118:121], v[146:149], v[186:189], v[118:121]
	v_mfma_f32_16x16x32_bf16 v[114:117], v[154:157], v[186:189], v[114:117]
	v_mfma_f32_16x16x32_bf16 v[102:105], v[146:149], v[194:197], v[102:105]
	v_mfma_f32_16x16x32_bf16 v[98:101], v[154:157], v[194:197], v[98:101]
	v_mfma_f32_16x16x32_bf16 v[86:89], v[146:149], v[202:205], v[86:89]
	v_mfma_f32_16x16x32_bf16 v[82:85], v[154:157], v[202:205], v[82:85]
	v_mfma_f32_16x16x32_bf16 v[70:73], v[146:149], v[210:213], v[70:73]
	v_mfma_f32_16x16x32_bf16 v[66:69], v[154:157], v[210:213], v[66:69]
	v_mfma_f32_16x16x32_bf16 v[118:121], v[150:153], v[190:193], v[118:121]
	v_mfma_f32_16x16x32_bf16 v[114:117], v[158:161], v[190:193], v[114:117]
	v_mfma_f32_16x16x32_bf16 v[102:105], v[150:153], v[198:201], v[102:105]
	v_mfma_f32_16x16x32_bf16 v[98:101], v[158:161], v[198:201], v[98:101]
	v_mfma_f32_16x16x32_bf16 v[86:89], v[150:153], v[206:209], v[86:89]
	v_mfma_f32_16x16x32_bf16 v[82:85], v[158:161], v[206:209], v[82:85]
	v_mfma_f32_16x16x32_bf16 v[70:73], v[150:153], v[214:217], v[70:73]
	v_mfma_f32_16x16x32_bf16 v[66:69], v[158:161], v[214:217], v[66:69]
	s_setprio 0
	s_barrier
	s_add_i32 s89, s89, s52
	v_lshl_add_u64 v[218:219], s[46:47], 0, v[0:1]
	s_mov_b32 m0, s89
	ds_read_b128 v[186:189], v241 offset:16384
	ds_read_b128 v[190:193], v241 offset:17408
	ds_read_b128 v[194:197], v241 offset:18432
	ds_read_b128 v[198:201], v241 offset:19456
	ds_read_b128 v[202:205], v241 offset:20480
	ds_read_b128 v[206:209], v241 offset:21504
	ds_read_b128 v[210:213], v241 offset:22528
	ds_read_b128 v[214:217], v241 offset:23552
	global_load_lds_dwordx4 v[218:219], off
	s_add_i32 m0, s89, 0x2000
	s_add_u32 vcc_lo, s46, 0x20000
	v_lshl_add_u64 v[220:221], s[46:47], 0, v[180:181]
	s_addc_u32 vcc_hi, s47, 0
	s_add_i32 s31, s31, s52
	global_load_lds_dwordx4 v[220:221], off
	v_lshl_add_u64 v[222:223], vcc, 0, v[0:1]
	s_mov_b32 m0, s31
	v_lshl_add_u64 v[224:225], s[48:49], 0, v[178:179]
	global_load_lds_dwordx4 v[222:223], off
	v_lshl_add_u64 v[222:223], vcc, 0, v[180:181]
	s_add_i32 m0, s31, 0x2000
	s_nop 0
	global_load_lds_dwordx4 v[222:223], off
	v_lshl_add_u64 v[222:223], s[48:49], 0, v[176:177]
	s_mov_b32 m0, s53
	s_nop 0
	global_load_lds_dwordx4 v[222:223], off
	s_mov_b32 m0, s54
	s_nop 0
	global_load_lds_dwordx4 v[224:225], off
	s_waitcnt vmcnt(8)
	s_waitcnt lgkmcnt(0)
	s_barrier
; #define PG8_STAGE(bufoff, gbase, voff) do { _Pragma("unroll") for (int _i = 0; _i < 2; ++_i) \
;         __builtin_amdgcn_global_load_lds((const unsigned*)((const char*)(gbase) + (voff)[_i]), (PG8_LAS unsigned*)(lds + (bufoff) + ldsw + _i * 8192), 16, 0, 0); } while (0)
; #define PG8_LDA(dst, b, h) do { _Pragma("unroll") for (int m = 0; m < 4; ++m) _Pragma("unroll") for (int k = 0; k < 2; ++k) dst[m][k] = *(const PG8_LAS bf16x8*)(lds + PG8_SA(b, h) + aoff + m * 2048 + k * 1024); } while (0)
; #define PG8_LDB(dst, b, h) do { _Pragma("unroll") for (int n = 0; n < 2; ++n) _Pragma("unroll") for (int k = 0; k < 2; ++k) dst[n][k] = *(const PG8_LAS bf16x8*)(lds + PG8_SB(b, h) + boff + n * 2048 + k * 1024); } while (0)
; #define PG8_MMA(ai, bj, At, Bt) do { __builtin_amdgcn_s_setprio(1); _Pragma("unroll") for (int m = 0; m < 4; ++m) _Pragma("unroll") for (int n = 0; n < 2; ++n) _Pragma("unroll") for (int k = 0; k < 2; ++k) \
;         acc[ai][bj][m][n] = __builtin_amdgcn_mfma_f32_16x16x32_bf16(Bt[n][k], At[m][k], acc[ai][bj][m][n], 0, 0, 0); __builtin_amdgcn_s_setprio(0); } while (0)
; #define PG8_WAIT_V(n) asm volatile("s_waitcnt vmcnt(" #n ")" ::: "memory")
; #define PG8_WAIT_L(n) asm volatile("s_waitcnt lgkmcnt(" #n ")" ::: "memory")
; #define PG8_BAR __builtin_amdgcn_s_barrier()
; #define PG8_SCHED __builtin_amdgcn_sched_barrier(0)
; template <class Epi, class Sched, bool ALIGN_EPI = false, bool SP2 = false>
; __device__ __forceinline__ void gemm_phase(PG8_LAS unsigned char* lds, const Gemm g, const Sched& S, const Epi& E, const int tid_in) {
;     ...
;             PG8_WAIT_V(8); PG8_WAIT_L(0); PG8_BAR; PG8_MMA(0, 0, At, B0); PG8_MMA(0, 1, At, B1); PG8_BAR; PG8_SCHED;
;             PG8_LDA(At, 0, 1); PG8_STAGE(PG8_SB(0, 0), b2, voffB); PG8_STAGE(PG8_SB(0, 1), b2 + hstep, voffB); PG8_STAGE(PG8_SA(0, 0), a2, voffA);
;             PG8_WAIT_V(8); PG8_WAIT_L(0); PG8_BAR; PG8_MMA(1, 0, At, B0); PG8_MMA(1, 1, At, B1); PG8_BAR; PG8_SCHED;
;             PG8_LDB(B0, 1, 0); PG8_LDB(B1, 1, 1); PG8_SCHED; PG8_LDA(At, 1, 0); PG8_STAGE(PG8_SA(0, 1), a2 + hstep, voffA);
;             PG8_WAIT_V(8); PG8_WAIT_L(0); PG8_BAR; PG8_MMA(0, 0, At, B0); PG8_MMA(0, 1, At, B1); PG8_BAR; PG8_SCHED;
	s_setprio 1
	s_waitcnt lgkmcnt(0)
	v_mfma_f32_16x16x32_bf16 v[62:65], v[130:133], v[186:189], v[62:65]
	v_mfma_f32_16x16x32_bf16 v[58:61], v[138:141], v[186:189], v[58:61]
	v_mfma_f32_16x16x32_bf16 v[46:49], v[130:133], v[194:197], v[46:49]
	v_mfma_f32_16x16x32_bf16 v[42:45], v[138:141], v[194:197], v[42:45]
	v_mfma_f32_16x16x32_bf16 v[30:33], v[130:133], v[202:205], v[30:33]
	v_mfma_f32_16x16x32_bf16 v[26:29], v[138:141], v[202:205], v[26:29]
	v_mfma_f32_16x16x32_bf16 v[14:17], v[130:133], v[210:213], v[14:17]
	v_mfma_f32_16x16x32_bf16 v[10:13], v[138:141], v[210:213], v[10:13]
	v_mfma_f32_16x16x32_bf16 v[62:65], v[134:137], v[190:193], v[62:65]
	v_mfma_f32_16x16x32_bf16 v[58:61], v[142:145], v[190:193], v[58:61]
	v_mfma_f32_16x16x32_bf16 v[46:49], v[134:137], v[198:201], v[46:49]
	v_mfma_f32_16x16x32_bf16 v[42:45], v[142:145], v[198:201], v[42:45]
	v_mfma_f32_16x16x32_bf16 v[30:33], v[134:137], v[206:209], v[30:33]
	v_mfma_f32_16x16x32_bf16 v[26:29], v[142:145], v[206:209], v[26:29]
	v_mfma_f32_16x16x32_bf16 v[14:17], v[134:137], v[214:217], v[14:17]
	v_mfma_f32_16x16x32_bf16 v[10:13], v[142:145], v[214:217], v[10:13]
	s_setprio 0
	s_setprio 1
	v_mfma_f32_16x16x32_bf16 v[54:57], v[146:149], v[186:189], v[54:57]
	v_mfma_f32_16x16x32_bf16 v[50:53], v[154:157], v[186:189], v[50:53]
	v_mfma_f32_16x16x32_bf16 v[38:41], v[146:149], v[194:197], v[38:41]
	v_mfma_f32_16x16x32_bf16 v[34:37], v[154:157], v[194:197], v[34:37]
	v_mfma_f32_16x16x32_bf16 v[22:25], v[146:149], v[202:205], v[22:25]
	v_mfma_f32_16x16x32_bf16 v[18:21], v[154:157], v[202:205], v[18:21]
	v_mfma_f32_16x16x32_bf16 v[6:9], v[146:149], v[210:213], v[6:9]
	v_mfma_f32_16x16x32_bf16 v[2:5], v[154:157], v[210:213], v[2:5]
	v_mfma_f32_16x16x32_bf16 v[54:57], v[150:153], v[190:193], v[54:57]
	v_mfma_f32_16x16x32_bf16 v[50:53], v[158:161], v[190:193], v[50:53]
	v_mfma_f32_16x16x32_bf16 v[38:41], v[150:153], v[198:201], v[38:41]
	v_mfma_f32_16x16x32_bf16 v[34:37], v[158:161], v[198:201], v[34:37]
	v_mfma_f32_16x16x32_bf16 v[22:25], v[150:153], v[206:209], v[22:25]
	v_mfma_f32_16x16x32_bf16 v[18:21], v[158:161], v[206:209], v[18:21]
	v_mfma_f32_16x16x32_bf16 v[6:9], v[150:153], v[214:217], v[6:9]
	v_mfma_f32_16x16x32_bf16 v[2:5], v[158:161], v[214:217], v[2:5]
	s_setprio 0
	s_barrier
	s_add_i32 s31, 0, 0x18000
	s_add_i32 s89, 0, 0x1c000
	v_add_u32_e32 v142, s31, v240
	v_add_u32_e32 v158, s89, v240
	ds_read_b128 v[130:133], v142
	ds_read_b128 v[134:137], v142 offset:1024
	ds_read_b128 v[138:141], v142 offset:2048
	ds_read_b128 v[142:145], v142 offset:3072
	ds_read_b128 v[146:149], v158
	ds_read_b128 v[150:153], v158 offset:1024
	ds_read_b128 v[154:157], v158 offset:2048
	ds_read_b128 v[158:161], v158 offset:3072
	s_add_u32 s48, s48, 0x20000
	s_addc_u32 s49, s49, 0
	s_mov_b32 m0, s55
	v_lshl_add_u64 v[226:227], s[48:49], 0, v[176:177]
	ds_read_b128 v[186:189], v241 offset:32768
	ds_read_b128 v[190:193], v241 offset:33792
	ds_read_b128 v[194:197], v241 offset:34816
	ds_read_b128 v[198:201], v241 offset:35840
	ds_read_b128 v[202:205], v241 offset:36864
	ds_read_b128 v[206:209], v241 offset:37888
	ds_read_b128 v[210:213], v241 offset:38912
	ds_read_b128 v[214:217], v241 offset:39936
	global_load_lds_dwordx4 v[226:227], off
	v_lshl_add_u64 v[226:227], s[48:49], 0, v[178:179]
	s_mov_b32 m0, s62
	s_nop 0
	global_load_lds_dwordx4 v[226:227], off
	s_waitcnt vmcnt(8)
	s_waitcnt lgkmcnt(0)
	s_barrier
	s_setprio 1
	s_waitcnt lgkmcnt(0)
	v_mfma_f32_16x16x32_bf16 v[126:129], v[130:133], v[186:189], v[126:129]
	v_mfma_f32_16x16x32_bf16 v[122:125], v[138:141], v[186:189], v[122:125]
	v_mfma_f32_16x16x32_bf16 v[110:113], v[130:133], v[194:197], v[110:113]
	v_mfma_f32_16x16x32_bf16 v[106:109], v[138:141], v[194:197], v[106:109]
	v_mfma_f32_16x16x32_bf16 v[94:97], v[130:133], v[202:205], v[94:97]
	v_mfma_f32_16x16x32_bf16 v[90:93], v[138:141], v[202:205], v[90:93]
	v_mfma_f32_16x16x32_bf16 v[78:81], v[130:133], v[210:213], v[78:81]
	v_mfma_f32_16x16x32_bf16 v[74:77], v[138:141], v[210:213], v[74:77]
	v_mfma_f32_16x16x32_bf16 v[126:129], v[134:137], v[190:193], v[126:129]
	v_mfma_f32_16x16x32_bf16 v[122:125], v[142:145], v[190:193], v[122:125]
	v_mfma_f32_16x16x32_bf16 v[110:113], v[134:137], v[198:201], v[110:113]
	v_mfma_f32_16x16x32_bf16 v[106:109], v[142:145], v[198:201], v[106:109]
	v_mfma_f32_16x16x32_bf16 v[94:97], v[134:137], v[206:209], v[94:97]
	v_mfma_f32_16x16x32_bf16 v[90:93], v[142:145], v[206:209], v[90:93]
	v_mfma_f32_16x16x32_bf16 v[78:81], v[134:137], v[214:217], v[78:81]
	v_mfma_f32_16x16x32_bf16 v[74:77], v[142:145], v[214:217], v[74:77]
	s_setprio 0
	s_setprio 1
	v_mfma_f32_16x16x32_bf16 v[118:121], v[146:149], v[186:189], v[118:121]
	v_mfma_f32_16x16x32_bf16 v[114:117], v[154:157], v[186:189], v[114:117]
	v_mfma_f32_16x16x32_bf16 v[102:105], v[146:149], v[194:197], v[102:105]
	v_mfma_f32_16x16x32_bf16 v[98:101], v[154:157], v[194:197], v[98:101]
	v_mfma_f32_16x16x32_bf16 v[86:89], v[146:149], v[202:205], v[86:89]
	v_mfma_f32_16x16x32_bf16 v[82:85], v[154:157], v[202:205], v[82:85]
	v_mfma_f32_16x16x32_bf16 v[70:73], v[146:149], v[210:213], v[70:73]
	v_mfma_f32_16x16x32_bf16 v[66:69], v[154:157], v[210:213], v[66:69]
	v_mfma_f32_16x16x32_bf16 v[118:121], v[150:153], v[190:193], v[118:121]
	v_mfma_f32_16x16x32_bf16 v[114:117], v[158:161], v[190:193], v[114:117]
	v_mfma_f32_16x16x32_bf16 v[102:105], v[150:153], v[198:201], v[102:105]
	v_mfma_f32_16x16x32_bf16 v[98:101], v[158:161], v[198:201], v[98:101]
	v_mfma_f32_16x16x32_bf16 v[86:89], v[150:153], v[206:209], v[86:89]
	v_mfma_f32_16x16x32_bf16 v[82:85], v[158:161], v[206:209], v[82:85]
	v_mfma_f32_16x16x32_bf16 v[70:73], v[150:153], v[214:217], v[70:73]
	v_mfma_f32_16x16x32_bf16 v[66:69], v[158:161], v[214:217], v[66:69]
	s_setprio 0
	s_barrier
; #define PG8_STAGE(bufoff, gbase, voff) do { _Pragma("unroll") for (int _i = 0; _i < 2; ++_i) \
;         __builtin_amdgcn_global_load_lds((const unsigned*)((const char*)(gbase) + (voff)[_i]), (PG8_LAS unsigned*)(lds + (bufoff) + ldsw + _i * 8192), 16, 0, 0); } while (0)
; #define PG8_LDA(dst, b, h) do { _Pragma("unroll") for (int m = 0; m < 4; ++m) _Pragma("unroll") for (int k = 0; k < 2; ++k) dst[m][k] = *(const PG8_LAS bf16x8*)(lds + PG8_SA(b, h) + aoff + m * 2048 + k * 1024); } while (0)
; #define PG8_MMA(ai, bj, At, Bt) do { __builtin_amdgcn_s_setprio(1); _Pragma("unroll") for (int m = 0; m < 4; ++m) _Pragma("unroll") for (int n = 0; n < 2; ++n) _Pragma("unroll") for (int k = 0; k < 2; ++k) \
;         acc[ai][bj][m][n] = __builtin_amdgcn_mfma_f32_16x16x32_bf16(Bt[n][k], At[m][k], acc[ai][bj][m][n], 0, 0, 0); __builtin_amdgcn_s_setprio(0); } while (0)
; #define PG8_WAIT_V(n) asm volatile("s_waitcnt vmcnt(" #n ")" ::: "memory")
; #define PG8_WAIT_L(n) asm volatile("s_waitcnt lgkmcnt(" #n ")" ::: "memory")
; #define PG8_BAR __builtin_amdgcn_s_barrier()
; #define PG8_SCHED __builtin_amdgcn_sched_barrier(0)
; template <class Epi, class Sched, bool ALIGN_EPI = false, bool SP2 = false>
; __device__ __forceinline__ void gemm_phase(PG8_LAS unsigned char* lds, const Gemm g, const Sched& S, const Epi& E, const int tid_in) {
;     ...
;             PG8_LDA(At, 1, 1); PG8_STAGE(PG8_SB(1, 0), b3, voffB); PG8_STAGE(PG8_SB(1, 1), b3 + hstep, voffB); PG8_STAGE(PG8_SA(1, 0), a3, voffA);
;             PG8_WAIT_V(8); PG8_WAIT_L(0); PG8_BAR; PG8_MMA(1, 0, At, B0); PG8_MMA(1, 1, At, B1); PG8_BAR; PG8_SCHED;
;     ...
;         if constexpr (ALIGN_EPI) { if (wr == 0) PG8_BAR; }
	s_add_i32 s31, s31, s52
	v_lshl_add_u64 v[218:219], v[218:219], 0, s[64:65]
	s_mov_b32 m0, s31
	ds_read_b128 v[186:189], v241 offset:49152
	ds_read_b128 v[190:193], v241 offset:50176
	ds_read_b128 v[194:197], v241 offset:51200
	ds_read_b128 v[198:201], v241 offset:52224
	ds_read_b128 v[202:205], v241 offset:53248
	ds_read_b128 v[206:209], v241 offset:54272
	ds_read_b128 v[210:213], v241 offset:55296
	ds_read_b128 v[214:217], v241 offset:56320
	global_load_lds_dwordx4 v[218:219], off
	s_add_i32 m0, s31, 0x2000
	s_add_u32 s46, s46, 0x20080
	v_lshl_add_u64 v[218:219], v[220:221], 0, s[64:65]
	s_addc_u32 s47, s47, 0
	s_add_i32 s31, s89, s52
	global_load_lds_dwordx4 v[218:219], off
	v_lshl_add_u64 v[218:219], s[46:47], 0, v[0:1]
	s_mov_b32 m0, s31
	s_nop 0
	global_load_lds_dwordx4 v[218:219], off
	v_lshl_add_u64 v[218:219], s[46:47], 0, v[180:181]
	s_add_i32 m0, s31, 0x2000
	s_nop 0
	global_load_lds_dwordx4 v[218:219], off
	v_lshl_add_u64 v[218:219], v[222:223], 0, s[64:65]
	s_mov_b32 m0, s83
	s_nop 0
	global_load_lds_dwordx4 v[218:219], off
	v_lshl_add_u64 v[218:219], v[224:225], 0, s[64:65]
	s_mov_b32 m0, s84
	s_nop 0
	global_load_lds_dwordx4 v[218:219], off
	s_waitcnt vmcnt(8)
	s_waitcnt lgkmcnt(0)
	s_barrier
	s_setprio 1
	s_waitcnt lgkmcnt(0)
	v_mfma_f32_16x16x32_bf16 v[62:65], v[130:133], v[186:189], v[62:65]
	v_mfma_f32_16x16x32_bf16 v[58:61], v[138:141], v[186:189], v[58:61]
	v_mfma_f32_16x16x32_bf16 v[46:49], v[130:133], v[194:197], v[46:49]
	v_mfma_f32_16x16x32_bf16 v[42:45], v[138:141], v[194:197], v[42:45]
	v_mfma_f32_16x16x32_bf16 v[30:33], v[130:133], v[202:205], v[30:33]
	v_mfma_f32_16x16x32_bf16 v[26:29], v[138:141], v[202:205], v[26:29]
	v_mfma_f32_16x16x32_bf16 v[14:17], v[130:133], v[210:213], v[14:17]
	v_mfma_f32_16x16x32_bf16 v[10:13], v[138:141], v[210:213], v[10:13]
	v_mfma_f32_16x16x32_bf16 v[62:65], v[134:137], v[190:193], v[62:65]
	v_mfma_f32_16x16x32_bf16 v[58:61], v[142:145], v[190:193], v[58:61]
	v_mfma_f32_16x16x32_bf16 v[46:49], v[134:137], v[198:201], v[46:49]
	v_mfma_f32_16x16x32_bf16 v[42:45], v[142:145], v[198:201], v[42:45]
	v_mfma_f32_16x16x32_bf16 v[30:33], v[134:137], v[206:209], v[30:33]
	v_mfma_f32_16x16x32_bf16 v[26:29], v[142:145], v[206:209], v[26:29]
	v_mfma_f32_16x16x32_bf16 v[14:17], v[134:137], v[214:217], v[14:17]
	v_mfma_f32_16x16x32_bf16 v[10:13], v[142:145], v[214:217], v[10:13]
	s_setprio 0
	s_setprio 1
	v_mfma_f32_16x16x32_bf16 v[54:57], v[146:149], v[186:189], v[54:57]
	v_mfma_f32_16x16x32_bf16 v[50:53], v[154:157], v[186:189], v[50:53]
	v_mfma_f32_16x16x32_bf16 v[38:41], v[146:149], v[194:197], v[38:41]
	v_mfma_f32_16x16x32_bf16 v[34:37], v[154:157], v[194:197], v[34:37]
	v_mfma_f32_16x16x32_bf16 v[22:25], v[146:149], v[202:205], v[22:25]
	v_mfma_f32_16x16x32_bf16 v[18:21], v[154:157], v[202:205], v[18:21]
	v_mfma_f32_16x16x32_bf16 v[6:9], v[146:149], v[210:213], v[6:9]
	v_mfma_f32_16x16x32_bf16 v[2:5], v[154:157], v[210:213], v[2:5]
	v_mfma_f32_16x16x32_bf16 v[54:57], v[150:153], v[190:193], v[54:57]
	v_mfma_f32_16x16x32_bf16 v[50:53], v[158:161], v[190:193], v[50:53]
	v_mfma_f32_16x16x32_bf16 v[38:41], v[150:153], v[198:201], v[38:41]
	v_mfma_f32_16x16x32_bf16 v[34:37], v[158:161], v[198:201], v[34:37]
	v_mfma_f32_16x16x32_bf16 v[22:25], v[150:153], v[206:209], v[22:25]
	v_mfma_f32_16x16x32_bf16 v[18:21], v[158:161], v[206:209], v[18:21]
	v_mfma_f32_16x16x32_bf16 v[6:9], v[150:153], v[214:217], v[6:9]
	v_mfma_f32_16x16x32_bf16 v[2:5], v[158:161], v[214:217], v[2:5]
	s_setprio 0
	s_barrier
	s_add_i32 s88, s88, 2
	s_add_u32 s44, s44, 0x100
	s_addc_u32 s45, s45, 0
	s_add_u32 s72, s72, 0x100
	s_addc_u32 s87, s87, 0
	s_cmp_gt_u32 s88, 5
	s_cbranch_scc0 .LBB0_86
	s_and_b64 vcc, exec, s[16:17]
	s_cbranch_vccz .LBB0_89
	s_barrier

; template <class Epi, class Sched, bool ALIGN_EPI = false, bool SP2 = false>
; __device__ __forceinline__ void gemm_phase(PG8_LAS unsigned char* lds, const Gemm g, const Sched& S, const Epi& E, const int tid_in) {
;     ...
;         const char* nA = has_next ? (const char*)g.A + (size_t)nxt.pm * tstep : cA; const char* nB = has_next ? (const char*)g.Bt + (size_t)nxt.pn * tstep : cB;
;         for (int t = 0; t < nt; t += 2) {
;             const bool last = (t == nt - 2);
;             const char* a1 = cA + (size_t)(t + 1) * kstep;
;             const char* a2 = last ? nA : cA + (size_t)(t + 2) * kstep; const char* b2 = last ? nB : cB + (size_t)(t + 2) * kstep;
;             const char* a3 = a2 + kstep; const char* b3 = b2 + kstep;
;     ...
;         for (int a = 0; a < 2; ++a)
; #pragma unroll
;             for (int b = 0; b < 2; ++b)
; #pragma unroll
;                 for (int m = 0; m < 4; ++m)
; #pragma unroll
;                     for (int n = 0; n < 2; ++n) acc[a][b][m][n] = (f32x4){0.f, 0.f, 0.f, 0.f};
.LBB0_1185:
	s_ashr_i32 s37, s36, 31
	s_lshl_b64 s[38:39], s[36:37], 20
	s_add_u32 s38, s25, s38
	s_addc_u32 s39, s34, s39
	s_and_b64 s[40:41], s[6:7], exec
	s_cselect_b32 s9, s39, s45
	s_cselect_b32 s37, s38, s44
	s_ashr_i32 s27, s26, 31
	s_lshl_b64 s[40:41], s[26:27], 20
	s_add_u32 s40, s10, s40
	s_addc_u32 s41, s11, s41
	s_and_b64 s[48:49], s[6:7], exec
	s_cselect_b32 s27, s41, s47
	s_cselect_b32 s72, s40, s46
	s_add_u32 s44, s44, 0x80080
	s_addc_u32 s45, s45, 0
	s_add_u32 s73, s46, 0x100
	v_mov_b32_e32 v2, 0
	s_addc_u32 s83, s47, 0
	s_mov_b32 s84, -2
	v_mov_b32_e32 v3, v2
	v_mov_b32_e32 v4, v2
	v_mov_b32_e32 v5, v2
	v_mov_b32_e32 v6, v2
	v_mov_b32_e32 v7, v2
	v_mov_b32_e32 v8, v2
	v_mov_b32_e32 v9, v2
	v_mov_b32_e32 v14, v2
	v_mov_b32_e32 v15, v2
	v_mov_b32_e32 v16, v2
	v_mov_b32_e32 v17, v2
	v_mov_b32_e32 v22, v2
	v_mov_b32_e32 v23, v2
	v_mov_b32_e32 v24, v2
	v_mov_b32_e32 v25, v2
	v_mov_b32_e32 v30, v2
	v_mov_b32_e32 v31, v2
	v_mov_b32_e32 v32, v2
	v_mov_b32_e32 v33, v2
	v_mov_b32_e32 v38, v2
	v_mov_b32_e32 v39, v2
	v_mov_b32_e32 v40, v2
	v_mov_b32_e32 v41, v2
	v_mov_b32_e32 v46, v2
	v_mov_b32_e32 v47, v2
	v_mov_b32_e32 v48, v2
	v_mov_b32_e32 v49, v2
	v_mov_b32_e32 v54, v2
	v_mov_b32_e32 v55, v2
	v_mov_b32_e32 v56, v2
	v_mov_b32_e32 v57, v2
	v_mov_b32_e32 v10, v2
	v_mov_b32_e32 v11, v2
	v_mov_b32_e32 v12, v2
	v_mov_b32_e32 v13, v2
	v_mov_b32_e32 v18, v2
	v_mov_b32_e32 v19, v2
	v_mov_b32_e32 v20, v2
	v_mov_b32_e32 v21, v2
	v_mov_b32_e32 v26, v2
	v_mov_b32_e32 v27, v2
	v_mov_b32_e32 v28, v2
	v_mov_b32_e32 v29, v2
	v_mov_b32_e32 v34, v2
	v_mov_b32_e32 v35, v2
	v_mov_b32_e32 v36, v2
	v_mov_b32_e32 v37, v2
	v_mov_b32_e32 v42, v2
	v_mov_b32_e32 v43, v2
	v_mov_b32_e32 v44, v2
	v_mov_b32_e32 v45, v2
	v_mov_b32_e32 v50, v2
	v_mov_b32_e32 v51, v2
	v_mov_b32_e32 v52, v2
	v_mov_b32_e32 v53, v2
	v_mov_b32_e32 v58, v2
	v_mov_b32_e32 v59, v2
	v_mov_b32_e32 v60, v2
	v_mov_b32_e32 v61, v2
	v_mov_b32_e32 v62, v2
	v_mov_b32_e32 v63, v2
	v_mov_b32_e32 v64, v2
	v_mov_b32_e32 v65, v2
	v_mov_b32_e32 v66, v2
	v_mov_b32_e32 v67, v2
	v_mov_b32_e32 v68, v2
	v_mov_b32_e32 v69, v2
	v_mov_b32_e32 v70, v2
	v_mov_b32_e32 v71, v2
	v_mov_b32_e32 v72, v2
	v_mov_b32_e32 v73, v2
	v_mov_b32_e32 v78, v2
	v_mov_b32_e32 v79, v2
	v_mov_b32_e32 v80, v2
	v_mov_b32_e32 v81, v2
	v_mov_b32_e32 v86, v2
	v_mov_b32_e32 v87, v2
	v_mov_b32_e32 v88, v2
	v_mov_b32_e32 v89, v2
	v_mov_b32_e32 v94, v2
	v_mov_b32_e32 v95, v2
	v_mov_b32_e32 v96, v2
	v_mov_b32_e32 v97, v2
	v_mov_b32_e32 v102, v2
	v_mov_b32_e32 v103, v2
	v_mov_b32_e32 v104, v2
	v_mov_b32_e32 v105, v2
	v_mov_b32_e32 v110, v2
	v_mov_b32_e32 v111, v2
	v_mov_b32_e32 v112, v2
	v_mov_b32_e32 v113, v2
	v_mov_b32_e32 v118, v2
	v_mov_b32_e32 v119, v2
	v_mov_b32_e32 v120, v2
	v_mov_b32_e32 v121, v2
	v_mov_b32_e32 v74, v2
	v_mov_b32_e32 v75, v2
	v_mov_b32_e32 v76, v2
	v_mov_b32_e32 v77, v2
	v_mov_b32_e32 v82, v2
	v_mov_b32_e32 v83, v2
	v_mov_b32_e32 v84, v2
	v_mov_b32_e32 v85, v2
	v_mov_b32_e32 v90, v2
	v_mov_b32_e32 v91, v2
	v_mov_b32_e32 v92, v2
	v_mov_b32_e32 v93, v2
	v_mov_b32_e32 v98, v2
	v_mov_b32_e32 v99, v2
	v_mov_b32_e32 v100, v2
	v_mov_b32_e32 v101, v2
	v_mov_b32_e32 v106, v2
	v_mov_b32_e32 v107, v2
	v_mov_b32_e32 v108, v2
	v_mov_b32_e32 v109, v2
	v_mov_b32_e32 v114, v2
	v_mov_b32_e32 v115, v2
	v_mov_b32_e32 v116, v2
	v_mov_b32_e32 v117, v2
	v_mov_b32_e32 v122, v2
	v_mov_b32_e32 v123, v2
	v_mov_b32_e32 v124, v2
	v_mov_b32_e32 v125, v2
	v_mov_b32_e32 v126, v2
	v_mov_b32_e32 v127, v2
	v_mov_b32_e32 v128, v2
	v_mov_b32_e32 v129, v2
	s_nop 0
	s_nop 0
	s_nop 0
	s_nop 0
	s_nop 0
	s_nop 0
	s_nop 0
	s_nop 0
	s_nop 0
	s_nop 0
	s_nop 0
	s_nop 0
	s_nop 0
	s_nop 0
	s_nop 0
	s_nop 0
	s_nop 0
	s_nop 0
	s_nop 0
	s_nop 0
	s_nop 0
	s_nop 0
	s_nop 0
	s_nop 0
	s_nop 0
	s_nop 0
	s_nop 0
